# prep_even window loads batched 8 deep; prep_odd prefix reads batched; odd-layer forget-gate columns by a thin MFMA routine so the projection runs exactly 6 rounds
# speedup vs baseline: 1.0419x; 1.0131x over previous
; DI void prep_odd(const Params& p, int j, char* smem) {
;     ...
;     part[tid5] = run;
;     __syncthreads();
;     float off = 0.f;
;     for (int i = 0; i < tid5; ++i) off += part[i];
; #pragma unroll
;     for (int i = 0; i < 16; ++i) FC[(size_t)seq * S_ + tid5 * 16 + i] = (off + loc[i]) * LOG2E;
.LBB0_903:
	v_mov_b32_e32 v23, s9
	ds_read_b128 v[96:99], v23
	ds_read_b128 v[100:103], v23 offset:16
	s_add_i32 s9, s9, 32
	s_mov_b64 s[98:99], exec
	s_waitcnt lgkmcnt(0)
	v_add_f32_e32 v0, v0, v96
	v_cmp_lt_u32_e32 vcc, 1, v3
	s_and_b64 exec, exec, vcc
	v_add_f32_e32 v0, v0, v97
	v_cmp_lt_u32_e32 vcc, 2, v3
	s_and_b64 exec, exec, vcc
	v_add_f32_e32 v0, v0, v98
	v_cmp_lt_u32_e32 vcc, 3, v3
	s_and_b64 exec, exec, vcc
	v_add_f32_e32 v0, v0, v99
	v_cmp_lt_u32_e32 vcc, 4, v3
	s_and_b64 exec, exec, vcc
	v_add_f32_e32 v0, v0, v100
	v_cmp_lt_u32_e32 vcc, 5, v3
	s_and_b64 exec, exec, vcc
	v_add_f32_e32 v0, v0, v101
	v_cmp_lt_u32_e32 vcc, 6, v3
	s_and_b64 exec, exec, vcc
	v_add_f32_e32 v0, v0, v102
	v_cmp_lt_u32_e32 vcc, 7, v3
	s_and_b64 exec, exec, vcc
	v_add_f32_e32 v0, v0, v103
	s_mov_b64 exec, s[98:99]
	v_cmp_ge_u32_e64 s[6:7], 8, v3
	v_add_u32_e32 v3, -8, v3
	s_or_b64 s[12:13], s[6:7], s[12:13]
	s_andn2_b64 exec, exec, s[12:13]
	s_cbranch_execnz .LBB0_903
	s_or_b64 exec, exec, s[12:13]
	s_branch .LBB0_900

; DI float bflo(unsigned v) { return __uint_as_float(v << 16); }
; DI float bfhi(unsigned v) { return __uint_as_float(v & 0xffff0000u); }
; DI void prep_even(const Params& p, int j, char* smem) {
;     ...
;         for (int i = 0; i < cnt; ++i) {
;           const uint2 v = *(const uint2*)(hr - (size_t)i * HLD + c0);
;           s0 += bflo(v.x); s1 += bfhi(v.x); s2 += bflo(v.y); s3 += bfhi(v.y);
;         }
;         const uint2 uu = *(const uint2*)(hr + c0);
;         const float ic = 1.f / (float)cnt;
;         uint2 o; o.x = pk2(s0 * ic - bflo(uu.x), s1 * ic - bfhi(uu.x)); o.y = pk2(s2 * ic - bflo(uu.y), s3 * ic - bfhi(uu.y));
;         *(uint2*)(DP + (size_t)tok * 1024 + c0) = o;
.LBB0_953:
	s_mov_b64 s[98:99], exec
	global_load_dwordx2 v[74:75], v[40:41], off
	v_lshl_add_u64 v[40:41], v[40:41], 0, s[16:17]
	v_cmp_gt_i32_e32 vcc, -1, v23
	s_and_b64 exec, exec, vcc
	global_load_dwordx2 v[76:77], v[40:41], off
	v_lshl_add_u64 v[40:41], v[40:41], 0, s[16:17]
	v_cmp_gt_i32_e32 vcc, -2, v23
	s_and_b64 exec, exec, vcc
	global_load_dwordx2 v[78:79], v[40:41], off
	v_lshl_add_u64 v[40:41], v[40:41], 0, s[16:17]
	v_cmp_gt_i32_e32 vcc, -3, v23
	s_and_b64 exec, exec, vcc
	global_load_dwordx2 v[80:81], v[40:41], off
	v_lshl_add_u64 v[40:41], v[40:41], 0, s[16:17]
	v_cmp_gt_i32_e32 vcc, -4, v23
	s_and_b64 exec, exec, vcc
	global_load_dwordx2 v[82:83], v[40:41], off
	v_lshl_add_u64 v[40:41], v[40:41], 0, s[16:17]
	v_cmp_gt_i32_e32 vcc, -5, v23
	s_and_b64 exec, exec, vcc
	global_load_dwordx2 v[84:85], v[40:41], off
	v_lshl_add_u64 v[40:41], v[40:41], 0, s[16:17]
	v_cmp_gt_i32_e32 vcc, -6, v23
	s_and_b64 exec, exec, vcc
	global_load_dwordx2 v[86:87], v[40:41], off
	v_lshl_add_u64 v[40:41], v[40:41], 0, s[16:17]
	v_cmp_gt_i32_e32 vcc, -7, v23
	s_and_b64 exec, exec, vcc
	global_load_dwordx2 v[88:89], v[40:41], off
	v_lshl_add_u64 v[40:41], v[40:41], 0, s[16:17]
	s_mov_b64 exec, s[98:99]
	s_waitcnt vmcnt(0)
	v_lshlrev_b32_e32 v66, 16, v74
	v_and_b32_e32 v67, 0xffff0000, v74
	v_lshlrev_b32_e32 v64, 16, v75
	v_and_b32_e32 v65, 0xffff0000, v75
	v_pk_add_f32 v[38:39], v[38:39], v[66:67]
	v_pk_add_f32 v[36:37], v[36:37], v[64:65]
	v_cmp_gt_i32_e32 vcc, -1, v23
	s_and_b64 exec, exec, vcc
	v_lshlrev_b32_e32 v66, 16, v76
	v_and_b32_e32 v67, 0xffff0000, v76
	v_lshlrev_b32_e32 v64, 16, v77
	v_and_b32_e32 v65, 0xffff0000, v77
	v_pk_add_f32 v[38:39], v[38:39], v[66:67]
	v_pk_add_f32 v[36:37], v[36:37], v[64:65]
	v_cmp_gt_i32_e32 vcc, -2, v23
	s_and_b64 exec, exec, vcc
	v_lshlrev_b32_e32 v66, 16, v78
	v_and_b32_e32 v67, 0xffff0000, v78
	v_lshlrev_b32_e32 v64, 16, v79
	v_and_b32_e32 v65, 0xffff0000, v79
	v_pk_add_f32 v[38:39], v[38:39], v[66:67]
	v_pk_add_f32 v[36:37], v[36:37], v[64:65]
	v_cmp_gt_i32_e32 vcc, -3, v23
	s_and_b64 exec, exec, vcc
	v_lshlrev_b32_e32 v66, 16, v80
	v_and_b32_e32 v67, 0xffff0000, v80
	v_lshlrev_b32_e32 v64, 16, v81
	v_and_b32_e32 v65, 0xffff0000, v81
	v_pk_add_f32 v[38:39], v[38:39], v[66:67]
	v_pk_add_f32 v[36:37], v[36:37], v[64:65]
	v_cmp_gt_i32_e32 vcc, -4, v23
	s_and_b64 exec, exec, vcc
	v_lshlrev_b32_e32 v66, 16, v82
	v_and_b32_e32 v67, 0xffff0000, v82
	v_lshlrev_b32_e32 v64, 16, v83
	v_and_b32_e32 v65, 0xffff0000, v83
	v_pk_add_f32 v[38:39], v[38:39], v[66:67]
	v_pk_add_f32 v[36:37], v[36:37], v[64:65]
	v_cmp_gt_i32_e32 vcc, -5, v23
	s_and_b64 exec, exec, vcc
	v_lshlrev_b32_e32 v66, 16, v84
	v_and_b32_e32 v67, 0xffff0000, v84
	v_lshlrev_b32_e32 v64, 16, v85
	v_and_b32_e32 v65, 0xffff0000, v85
	v_pk_add_f32 v[38:39], v[38:39], v[66:67]
	v_pk_add_f32 v[36:37], v[36:37], v[64:65]
	v_cmp_gt_i32_e32 vcc, -6, v23
	s_and_b64 exec, exec, vcc
	v_lshlrev_b32_e32 v66, 16, v86
	v_and_b32_e32 v67, 0xffff0000, v86
	v_lshlrev_b32_e32 v64, 16, v87
	v_and_b32_e32 v65, 0xffff0000, v87
	v_pk_add_f32 v[38:39], v[38:39], v[66:67]
	v_pk_add_f32 v[36:37], v[36:37], v[64:65]
	v_cmp_gt_i32_e32 vcc, -7, v23
	s_and_b64 exec, exec, vcc
	v_lshlrev_b32_e32 v66, 16, v88
	v_and_b32_e32 v67, 0xffff0000, v88
	v_lshlrev_b32_e32 v64, 16, v89
	v_and_b32_e32 v65, 0xffff0000, v89
	v_pk_add_f32 v[38:39], v[38:39], v[66:67]
	v_pk_add_f32 v[36:37], v[36:37], v[64:65]
	s_mov_b64 exec, s[98:99]
	v_add_u32_e32 v23, 8, v23
	v_cmp_le_i32_e32 vcc, 0, v23
	s_or_b64 s[14:15], vcc, s[14:15]
	s_andn2_b64 exec, exec, s[14:15]
	s_cbranch_execnz .LBB0_953
	s_or_b64 exec, exec, s[14:15]
	v_mov_b32_e32 v23, v1
	v_lshl_add_u64 v[34:35], v[34:35], 0, v[22:23]
	global_load_dwordx2 v[34:35], v[34:35], off
	v_and_b32_e32 v23, 0x1fff, v8
	v_add_u32_e32 v23, 1, v23
	v_min_u32_e32 v23, v23, v19
	v_cvt_f32_ubyte0_e32 v23, v23
	v_div_scale_f32 v25, s[14:15], v23, v23, 1.0
	v_rcp_f32_e32 v27, v25
	s_waitcnt vmcnt(0)
	v_lshlrev_b32_e32 v64, 16, v34
	v_fma_f32 v33, -v25, v27, 1.0
	v_fmac_f32_e32 v27, v33, v27
	v_div_scale_f32 v33, vcc, 1.0, v23, 1.0
	v_mul_f32_e32 v40, v33, v27
	v_fma_f32 v41, -v25, v40, v33
	v_fmac_f32_e32 v40, v41, v27
	v_fma_f32 v25, -v25, v40, v33
	v_div_fmas_f32 v25, v25, v27, v40
	v_div_fixup_f32 v40, v25, v23, 1.0
	v_and_b32_e32 v65, 0xffff0000, v34
	v_pk_fma_f32 v[38:39], v[40:41], v[38:39], v[64:65] op_sel_hi:[0,1,1] neg_lo:[0,0,1] neg_hi:[0,0,1]
	v_cvt_pk_bf16_f32 v34, v38, v39
	v_lshlrev_b32_e32 v38, 16, v35
	v_and_b32_e32 v39, 0xffff0000, v35
	v_pk_fma_f32 v[36:37], v[40:41], v[36:37], v[38:39] op_sel_hi:[0,1,1] neg_lo:[0,0,1] neg_hi:[0,0,1]
	v_cvt_pk_bf16_f32 v35, v36, v37
	v_lshlrev_b64 v[36:37], 11, v[8:9]
	v_lshl_add_u64 v[36:37], v[14:15], 0, v[36:37]
	global_store_dwordx2 v[36:37], v[34:35], off
	s_and_saveexec_b64 s[14:15], s[12:13]
	s_cbranch_execnz .LBB0_957
	s_or_b64 exec, exec, s[14:15]
	s_and_saveexec_b64 s[14:15], s[10:11]
	s_cbranch_execnz .LBB0_960

; DI float bflo(unsigned v) { return __uint_as_float(v << 16); }
; DI float bfhi(unsigned v) { return __uint_as_float(v & 0xffff0000u); }
; DI void prep_even(const Params& p, int j, char* smem) {
;     ...
;         for (int i = 0; i < cnt; ++i) {
;           const uint2 v = *(const uint2*)(hr - (size_t)i * HLD + c0);
;           s0 += bflo(v.x); s1 += bfhi(v.x); s2 += bflo(v.y); s3 += bfhi(v.y);
;         }
;         const uint2 uu = *(const uint2*)(hr + c0);
;         const float ic = 1.f / (float)cnt;
;         uint2 o; o.x = pk2(s0 * ic - bflo(uu.x), s1 * ic - bfhi(uu.x)); o.y = pk2(s2 * ic - bflo(uu.y), s3 * ic - bfhi(uu.y));
;         *(uint2*)(DP + (size_t)tok * 1024 + c0) = o;
.LBB0_958:
	s_mov_b64 s[98:99], exec
	global_load_dwordx2 v[74:75], v[38:39], off
	v_lshl_add_u64 v[38:39], v[38:39], 0, s[18:19]
	v_cmp_gt_i32_e32 vcc, -1, v9
	s_and_b64 exec, exec, vcc
	global_load_dwordx2 v[76:77], v[38:39], off
	v_lshl_add_u64 v[38:39], v[38:39], 0, s[18:19]
	v_cmp_gt_i32_e32 vcc, -2, v9
	s_and_b64 exec, exec, vcc
	global_load_dwordx2 v[78:79], v[38:39], off
	v_lshl_add_u64 v[38:39], v[38:39], 0, s[18:19]
	v_cmp_gt_i32_e32 vcc, -3, v9
	s_and_b64 exec, exec, vcc
	global_load_dwordx2 v[80:81], v[38:39], off
	v_lshl_add_u64 v[38:39], v[38:39], 0, s[18:19]
	v_cmp_gt_i32_e32 vcc, -4, v9
	s_and_b64 exec, exec, vcc
	global_load_dwordx2 v[82:83], v[38:39], off
	v_lshl_add_u64 v[38:39], v[38:39], 0, s[18:19]
	v_cmp_gt_i32_e32 vcc, -5, v9
	s_and_b64 exec, exec, vcc
	global_load_dwordx2 v[84:85], v[38:39], off
	v_lshl_add_u64 v[38:39], v[38:39], 0, s[18:19]
	v_cmp_gt_i32_e32 vcc, -6, v9
	s_and_b64 exec, exec, vcc
	global_load_dwordx2 v[86:87], v[38:39], off
	v_lshl_add_u64 v[38:39], v[38:39], 0, s[18:19]
	v_cmp_gt_i32_e32 vcc, -7, v9
	s_and_b64 exec, exec, vcc
	global_load_dwordx2 v[88:89], v[38:39], off
	v_lshl_add_u64 v[38:39], v[38:39], 0, s[18:19]
	s_mov_b64 exec, s[98:99]
	s_waitcnt vmcnt(0)
	v_lshlrev_b32_e32 v64, 16, v74
	v_and_b32_e32 v65, 0xffff0000, v74
	v_lshlrev_b32_e32 v40, 16, v75
	v_and_b32_e32 v41, 0xffff0000, v75
	v_pk_add_f32 v[36:37], v[36:37], v[64:65]
	v_pk_add_f32 v[34:35], v[34:35], v[40:41]
	v_cmp_gt_i32_e32 vcc, -1, v9
	s_and_b64 exec, exec, vcc
	v_lshlrev_b32_e32 v64, 16, v76
	v_and_b32_e32 v65, 0xffff0000, v76
	v_lshlrev_b32_e32 v40, 16, v77
	v_and_b32_e32 v41, 0xffff0000, v77
	v_pk_add_f32 v[36:37], v[36:37], v[64:65]
	v_pk_add_f32 v[34:35], v[34:35], v[40:41]
	v_cmp_gt_i32_e32 vcc, -2, v9
	s_and_b64 exec, exec, vcc
	v_lshlrev_b32_e32 v64, 16, v78
	v_and_b32_e32 v65, 0xffff0000, v78
	v_lshlrev_b32_e32 v40, 16, v79
	v_and_b32_e32 v41, 0xffff0000, v79
	v_pk_add_f32 v[36:37], v[36:37], v[64:65]
	v_pk_add_f32 v[34:35], v[34:35], v[40:41]
	v_cmp_gt_i32_e32 vcc, -3, v9
	s_and_b64 exec, exec, vcc
	v_lshlrev_b32_e32 v64, 16, v80
	v_and_b32_e32 v65, 0xffff0000, v80
	v_lshlrev_b32_e32 v40, 16, v81
	v_and_b32_e32 v41, 0xffff0000, v81
	v_pk_add_f32 v[36:37], v[36:37], v[64:65]
	v_pk_add_f32 v[34:35], v[34:35], v[40:41]
	v_cmp_gt_i32_e32 vcc, -4, v9
	s_and_b64 exec, exec, vcc
	v_lshlrev_b32_e32 v64, 16, v82
	v_and_b32_e32 v65, 0xffff0000, v82
	v_lshlrev_b32_e32 v40, 16, v83
	v_and_b32_e32 v41, 0xffff0000, v83
	v_pk_add_f32 v[36:37], v[36:37], v[64:65]
	v_pk_add_f32 v[34:35], v[34:35], v[40:41]
	v_cmp_gt_i32_e32 vcc, -5, v9
	s_and_b64 exec, exec, vcc
	v_lshlrev_b32_e32 v64, 16, v84
	v_and_b32_e32 v65, 0xffff0000, v84
	v_lshlrev_b32_e32 v40, 16, v85
	v_and_b32_e32 v41, 0xffff0000, v85
	v_pk_add_f32 v[36:37], v[36:37], v[64:65]
	v_pk_add_f32 v[34:35], v[34:35], v[40:41]
	v_cmp_gt_i32_e32 vcc, -6, v9
	s_and_b64 exec, exec, vcc
	v_lshlrev_b32_e32 v64, 16, v86
	v_and_b32_e32 v65, 0xffff0000, v86
	v_lshlrev_b32_e32 v40, 16, v87
	v_and_b32_e32 v41, 0xffff0000, v87
	v_pk_add_f32 v[36:37], v[36:37], v[64:65]
	v_pk_add_f32 v[34:35], v[34:35], v[40:41]
	v_cmp_gt_i32_e32 vcc, -7, v9
	s_and_b64 exec, exec, vcc
	v_lshlrev_b32_e32 v64, 16, v88
	v_and_b32_e32 v65, 0xffff0000, v88
	v_lshlrev_b32_e32 v40, 16, v89
	v_and_b32_e32 v41, 0xffff0000, v89
	v_pk_add_f32 v[36:37], v[36:37], v[64:65]
	v_pk_add_f32 v[34:35], v[34:35], v[40:41]
	s_mov_b64 exec, s[98:99]
	v_add_u32_e32 v9, 8, v9
	v_cmp_le_i32_e32 vcc, 0, v9
	s_or_b64 s[16:17], vcc, s[16:17]
	s_andn2_b64 exec, exec, s[16:17]
	s_cbranch_execnz .LBB0_958
	s_or_b64 exec, exec, s[16:17]
	s_movk_i32 s16, 0x2a00
	v_mad_i64_i32 v[38:39], s[16:17], v32, s16, v[16:17]
	global_load_dwordx2 v[38:39], v[38:39], off
	v_and_b32_e32 v9, 0x1fff, v32
	v_add_u32_e32 v9, 1, v9
	v_min_u32_e32 v9, v9, v19
	v_cvt_f32_ubyte0_e32 v9, v9
	v_div_scale_f32 v23, s[16:17], v9, v9, 1.0
	v_rcp_f32_e32 v25, v23
	v_ashrrev_i32_e32 v33, 31, v32
	v_fma_f32 v27, -v23, v25, 1.0
	v_fmac_f32_e32 v25, v27, v25
	v_div_scale_f32 v27, vcc, 1.0, v9, 1.0
	v_mul_f32_e32 v40, v27, v25
	v_fma_f32 v41, -v23, v40, v27
	v_fmac_f32_e32 v40, v41, v25
	v_fma_f32 v23, -v23, v40, v27
	v_div_fmas_f32 v23, v23, v25, v40
	v_div_fixup_f32 v40, v23, v9, 1.0
	s_waitcnt vmcnt(0)
	v_lshlrev_b32_e32 v64, 16, v38
	v_and_b32_e32 v65, 0xffff0000, v38
	v_lshlrev_b32_e32 v38, 16, v39
	v_and_b32_e32 v39, 0xffff0000, v39
	v_pk_fma_f32 v[36:37], v[40:41], v[36:37], v[64:65] op_sel_hi:[0,1,1] neg_lo:[0,0,1] neg_hi:[0,0,1]
	v_pk_fma_f32 v[34:35], v[40:41], v[34:35], v[38:39] op_sel_hi:[0,1,1] neg_lo:[0,0,1] neg_hi:[0,0,1]
	v_cvt_pk_bf16_f32 v36, v36, v37
	v_cvt_pk_bf16_f32 v37, v34, v35
	v_lshlrev_b64 v[34:35], 11, v[32:33]
	v_lshl_add_u64 v[34:35], v[14:15], 0, v[34:35]
	global_store_dwordx2 v[34:35], v[36:37], off
	s_or_b64 exec, exec, s[14:15]
	s_and_saveexec_b64 s[14:15], s[10:11]
	s_cbranch_execz .LBB0_956

; DI float bflo(unsigned v) { return __uint_as_float(v << 16); }
; DI float bfhi(unsigned v) { return __uint_as_float(v & 0xffff0000u); }
; DI void prep_even(const Params& p, int j, char* smem) {
;     ...
;         for (int i = 0; i < cnt; ++i) {
;           const uint2 v = *(const uint2*)(hr - (size_t)i * HLD + c0);
;           s0 += bflo(v.x); s1 += bfhi(v.x); s2 += bflo(v.y); s3 += bfhi(v.y);
;         }
;         const uint2 uu = *(const uint2*)(hr + c0);
;         const float ic = 1.f / (float)cnt;
;         uint2 o; o.x = pk2(s0 * ic - bflo(uu.x), s1 * ic - bfhi(uu.x)); o.y = pk2(s2 * ic - bflo(uu.y), s3 * ic - bfhi(uu.y));
;         *(uint2*)(DP + (size_t)tok * 1024 + c0) = o;
.LBB0_961:
	s_mov_b64 s[98:99], exec
	global_load_dwordx2 v[74:75], v[38:39], off
	v_lshl_add_u64 v[38:39], v[38:39], 0, s[18:19]
	v_cmp_gt_i32_e32 vcc, -1, v9
	s_and_b64 exec, exec, vcc
	global_load_dwordx2 v[76:77], v[38:39], off
	v_lshl_add_u64 v[38:39], v[38:39], 0, s[18:19]
	v_cmp_gt_i32_e32 vcc, -2, v9
	s_and_b64 exec, exec, vcc
	global_load_dwordx2 v[78:79], v[38:39], off
	v_lshl_add_u64 v[38:39], v[38:39], 0, s[18:19]
	v_cmp_gt_i32_e32 vcc, -3, v9
	s_and_b64 exec, exec, vcc
	global_load_dwordx2 v[80:81], v[38:39], off
	v_lshl_add_u64 v[38:39], v[38:39], 0, s[18:19]
	v_cmp_gt_i32_e32 vcc, -4, v9
	s_and_b64 exec, exec, vcc
	global_load_dwordx2 v[82:83], v[38:39], off
	v_lshl_add_u64 v[38:39], v[38:39], 0, s[18:19]
	v_cmp_gt_i32_e32 vcc, -5, v9
	s_and_b64 exec, exec, vcc
	global_load_dwordx2 v[84:85], v[38:39], off
	v_lshl_add_u64 v[38:39], v[38:39], 0, s[18:19]
	v_cmp_gt_i32_e32 vcc, -6, v9
	s_and_b64 exec, exec, vcc
	global_load_dwordx2 v[86:87], v[38:39], off
	v_lshl_add_u64 v[38:39], v[38:39], 0, s[18:19]
	v_cmp_gt_i32_e32 vcc, -7, v9
	s_and_b64 exec, exec, vcc
	global_load_dwordx2 v[88:89], v[38:39], off
	v_lshl_add_u64 v[38:39], v[38:39], 0, s[18:19]
	s_mov_b64 exec, s[98:99]
	s_waitcnt vmcnt(0)
	v_lshlrev_b32_e32 v64, 16, v74
	v_and_b32_e32 v65, 0xffff0000, v74
	v_lshlrev_b32_e32 v40, 16, v75
	v_and_b32_e32 v41, 0xffff0000, v75
	v_pk_add_f32 v[36:37], v[36:37], v[64:65]
	v_pk_add_f32 v[34:35], v[34:35], v[40:41]
	v_cmp_gt_i32_e32 vcc, -1, v9
	s_and_b64 exec, exec, vcc
	v_lshlrev_b32_e32 v64, 16, v76
	v_and_b32_e32 v65, 0xffff0000, v76
	v_lshlrev_b32_e32 v40, 16, v77
	v_and_b32_e32 v41, 0xffff0000, v77
	v_pk_add_f32 v[36:37], v[36:37], v[64:65]
	v_pk_add_f32 v[34:35], v[34:35], v[40:41]
	v_cmp_gt_i32_e32 vcc, -2, v9
	s_and_b64 exec, exec, vcc
	v_lshlrev_b32_e32 v64, 16, v78
	v_and_b32_e32 v65, 0xffff0000, v78
	v_lshlrev_b32_e32 v40, 16, v79
	v_and_b32_e32 v41, 0xffff0000, v79
	v_pk_add_f32 v[36:37], v[36:37], v[64:65]
	v_pk_add_f32 v[34:35], v[34:35], v[40:41]
	v_cmp_gt_i32_e32 vcc, -3, v9
	s_and_b64 exec, exec, vcc
	v_lshlrev_b32_e32 v64, 16, v80
	v_and_b32_e32 v65, 0xffff0000, v80
	v_lshlrev_b32_e32 v40, 16, v81
	v_and_b32_e32 v41, 0xffff0000, v81
	v_pk_add_f32 v[36:37], v[36:37], v[64:65]
	v_pk_add_f32 v[34:35], v[34:35], v[40:41]
	v_cmp_gt_i32_e32 vcc, -4, v9
	s_and_b64 exec, exec, vcc
	v_lshlrev_b32_e32 v64, 16, v82
	v_and_b32_e32 v65, 0xffff0000, v82
	v_lshlrev_b32_e32 v40, 16, v83
	v_and_b32_e32 v41, 0xffff0000, v83
	v_pk_add_f32 v[36:37], v[36:37], v[64:65]
	v_pk_add_f32 v[34:35], v[34:35], v[40:41]
	v_cmp_gt_i32_e32 vcc, -5, v9
	s_and_b64 exec, exec, vcc
	v_lshlrev_b32_e32 v64, 16, v84
	v_and_b32_e32 v65, 0xffff0000, v84
	v_lshlrev_b32_e32 v40, 16, v85
	v_and_b32_e32 v41, 0xffff0000, v85
	v_pk_add_f32 v[36:37], v[36:37], v[64:65]
	v_pk_add_f32 v[34:35], v[34:35], v[40:41]
	v_cmp_gt_i32_e32 vcc, -6, v9
	s_and_b64 exec, exec, vcc
	v_lshlrev_b32_e32 v64, 16, v86
	v_and_b32_e32 v65, 0xffff0000, v86
	v_lshlrev_b32_e32 v40, 16, v87
	v_and_b32_e32 v41, 0xffff0000, v87
	v_pk_add_f32 v[36:37], v[36:37], v[64:65]
	v_pk_add_f32 v[34:35], v[34:35], v[40:41]
	v_cmp_gt_i32_e32 vcc, -7, v9
	s_and_b64 exec, exec, vcc
	v_lshlrev_b32_e32 v64, 16, v88
	v_and_b32_e32 v65, 0xffff0000, v88
	v_lshlrev_b32_e32 v40, 16, v89
	v_and_b32_e32 v41, 0xffff0000, v89
	v_pk_add_f32 v[36:37], v[36:37], v[64:65]
	v_pk_add_f32 v[34:35], v[34:35], v[40:41]
	s_mov_b64 exec, s[98:99]
	v_add_u32_e32 v9, 8, v9
	v_cmp_le_i32_e32 vcc, 0, v9
	s_or_b64 s[16:17], vcc, s[16:17]
	s_andn2_b64 exec, exec, s[16:17]
	s_cbranch_execnz .LBB0_961
	s_or_b64 exec, exec, s[16:17]
	s_movk_i32 s16, 0x2a00
	v_mad_i64_i32 v[38:39], s[16:17], v26, s16, v[16:17]
	global_load_dwordx2 v[38:39], v[38:39], off
	v_and_b32_e32 v9, 0x1fff, v26
	v_add_u32_e32 v9, 1, v9
	v_min_u32_e32 v9, v9, v19
	v_cvt_f32_ubyte0_e32 v9, v9
	v_div_scale_f32 v23, s[16:17], v9, v9, 1.0
	v_rcp_f32_e32 v25, v23
	v_ashrrev_i32_e32 v27, 31, v26
	v_fma_f32 v33, -v23, v25, 1.0
	v_fmac_f32_e32 v25, v33, v25
	v_div_scale_f32 v33, vcc, 1.0, v9, 1.0
	v_mul_f32_e32 v40, v33, v25
	v_fma_f32 v41, -v23, v40, v33
	v_fmac_f32_e32 v40, v41, v25
	v_fma_f32 v23, -v23, v40, v33
	v_div_fmas_f32 v23, v23, v25, v40
	v_div_fixup_f32 v40, v23, v9, 1.0
	s_waitcnt vmcnt(0)
	v_lshlrev_b32_e32 v64, 16, v38
	v_and_b32_e32 v65, 0xffff0000, v38
	v_lshlrev_b32_e32 v38, 16, v39
	v_and_b32_e32 v39, 0xffff0000, v39
	v_pk_fma_f32 v[36:37], v[40:41], v[36:37], v[64:65] op_sel_hi:[0,1,1] neg_lo:[0,0,1] neg_hi:[0,0,1]
	v_pk_fma_f32 v[34:35], v[40:41], v[34:35], v[38:39] op_sel_hi:[0,1,1] neg_lo:[0,0,1] neg_hi:[0,0,1]
	v_cvt_pk_bf16_f32 v36, v36, v37
	v_cvt_pk_bf16_f32 v37, v34, v35
	v_lshlrev_b64 v[34:35], 11, v[26:27]
	v_lshl_add_u64 v[34:35], v[14:15], 0, v[34:35]
	global_store_dwordx2 v[34:35], v[36:37], off
	s_or_b64 exec, exec, s[14:15]
	s_and_saveexec_b64 s[14:15], s[8:9]
	s_cbranch_execz .LBB0_966

; DI float bflo(unsigned v) { return __uint_as_float(v << 16); }
; DI float bfhi(unsigned v) { return __uint_as_float(v & 0xffff0000u); }
; DI void prep_even(const Params& p, int j, char* smem) {
;     ...
;         for (int i = 0; i < cnt; ++i) {
;           const uint2 v = *(const uint2*)(hr - (size_t)i * HLD + c0);
;           s0 += bflo(v.x); s1 += bfhi(v.x); s2 += bflo(v.y); s3 += bfhi(v.y);
;         }
;         const uint2 uu = *(const uint2*)(hr + c0);
;         const float ic = 1.f / (float)cnt;
;         uint2 o; o.x = pk2(s0 * ic - bflo(uu.x), s1 * ic - bfhi(uu.x)); o.y = pk2(s2 * ic - bflo(uu.y), s3 * ic - bfhi(uu.y));
;         *(uint2*)(DP + (size_t)tok * 1024 + c0) = o;
.LBB0_964:
	s_mov_b64 s[98:99], exec
	global_load_dwordx2 v[74:75], v[38:39], off
	v_lshl_add_u64 v[38:39], v[38:39], 0, s[18:19]
	v_cmp_gt_i32_e32 vcc, -1, v9
	s_and_b64 exec, exec, vcc
	global_load_dwordx2 v[76:77], v[38:39], off
	v_lshl_add_u64 v[38:39], v[38:39], 0, s[18:19]
	v_cmp_gt_i32_e32 vcc, -2, v9
	s_and_b64 exec, exec, vcc
	global_load_dwordx2 v[78:79], v[38:39], off
	v_lshl_add_u64 v[38:39], v[38:39], 0, s[18:19]
	v_cmp_gt_i32_e32 vcc, -3, v9
	s_and_b64 exec, exec, vcc
	global_load_dwordx2 v[80:81], v[38:39], off
	v_lshl_add_u64 v[38:39], v[38:39], 0, s[18:19]
	v_cmp_gt_i32_e32 vcc, -4, v9
	s_and_b64 exec, exec, vcc
	global_load_dwordx2 v[82:83], v[38:39], off
	v_lshl_add_u64 v[38:39], v[38:39], 0, s[18:19]
	v_cmp_gt_i32_e32 vcc, -5, v9
	s_and_b64 exec, exec, vcc
	global_load_dwordx2 v[84:85], v[38:39], off
	v_lshl_add_u64 v[38:39], v[38:39], 0, s[18:19]
	v_cmp_gt_i32_e32 vcc, -6, v9
	s_and_b64 exec, exec, vcc
	global_load_dwordx2 v[86:87], v[38:39], off
	v_lshl_add_u64 v[38:39], v[38:39], 0, s[18:19]
	v_cmp_gt_i32_e32 vcc, -7, v9
	s_and_b64 exec, exec, vcc
	global_load_dwordx2 v[88:89], v[38:39], off
	v_lshl_add_u64 v[38:39], v[38:39], 0, s[18:19]
	s_mov_b64 exec, s[98:99]
	s_waitcnt vmcnt(0)
	v_lshlrev_b32_e32 v64, 16, v74
	v_and_b32_e32 v65, 0xffff0000, v74
	v_lshlrev_b32_e32 v40, 16, v75
	v_and_b32_e32 v41, 0xffff0000, v75
	v_pk_add_f32 v[36:37], v[36:37], v[64:65]
	v_pk_add_f32 v[34:35], v[34:35], v[40:41]
	v_cmp_gt_i32_e32 vcc, -1, v9
	s_and_b64 exec, exec, vcc
	v_lshlrev_b32_e32 v64, 16, v76
	v_and_b32_e32 v65, 0xffff0000, v76
	v_lshlrev_b32_e32 v40, 16, v77
	v_and_b32_e32 v41, 0xffff0000, v77
	v_pk_add_f32 v[36:37], v[36:37], v[64:65]
	v_pk_add_f32 v[34:35], v[34:35], v[40:41]
	v_cmp_gt_i32_e32 vcc, -2, v9
	s_and_b64 exec, exec, vcc
	v_lshlrev_b32_e32 v64, 16, v78
	v_and_b32_e32 v65, 0xffff0000, v78
	v_lshlrev_b32_e32 v40, 16, v79
	v_and_b32_e32 v41, 0xffff0000, v79
	v_pk_add_f32 v[36:37], v[36:37], v[64:65]
	v_pk_add_f32 v[34:35], v[34:35], v[40:41]
	v_cmp_gt_i32_e32 vcc, -3, v9
	s_and_b64 exec, exec, vcc
	v_lshlrev_b32_e32 v64, 16, v80
	v_and_b32_e32 v65, 0xffff0000, v80
	v_lshlrev_b32_e32 v40, 16, v81
	v_and_b32_e32 v41, 0xffff0000, v81
	v_pk_add_f32 v[36:37], v[36:37], v[64:65]
	v_pk_add_f32 v[34:35], v[34:35], v[40:41]
	v_cmp_gt_i32_e32 vcc, -4, v9
	s_and_b64 exec, exec, vcc
	v_lshlrev_b32_e32 v64, 16, v82
	v_and_b32_e32 v65, 0xffff0000, v82
	v_lshlrev_b32_e32 v40, 16, v83
	v_and_b32_e32 v41, 0xffff0000, v83
	v_pk_add_f32 v[36:37], v[36:37], v[64:65]
	v_pk_add_f32 v[34:35], v[34:35], v[40:41]
	v_cmp_gt_i32_e32 vcc, -5, v9
	s_and_b64 exec, exec, vcc
	v_lshlrev_b32_e32 v64, 16, v84
	v_and_b32_e32 v65, 0xffff0000, v84
	v_lshlrev_b32_e32 v40, 16, v85
	v_and_b32_e32 v41, 0xffff0000, v85
	v_pk_add_f32 v[36:37], v[36:37], v[64:65]
	v_pk_add_f32 v[34:35], v[34:35], v[40:41]
	v_cmp_gt_i32_e32 vcc, -6, v9
	s_and_b64 exec, exec, vcc
	v_lshlrev_b32_e32 v64, 16, v86
	v_and_b32_e32 v65, 0xffff0000, v86
	v_lshlrev_b32_e32 v40, 16, v87
	v_and_b32_e32 v41, 0xffff0000, v87
	v_pk_add_f32 v[36:37], v[36:37], v[64:65]
	v_pk_add_f32 v[34:35], v[34:35], v[40:41]
	v_cmp_gt_i32_e32 vcc, -7, v9
	s_and_b64 exec, exec, vcc
	v_lshlrev_b32_e32 v64, 16, v88
	v_and_b32_e32 v65, 0xffff0000, v88
	v_lshlrev_b32_e32 v40, 16, v89
	v_and_b32_e32 v41, 0xffff0000, v89
	v_pk_add_f32 v[36:37], v[36:37], v[64:65]
	v_pk_add_f32 v[34:35], v[34:35], v[40:41]
	s_mov_b64 exec, s[98:99]
	v_add_u32_e32 v9, 8, v9
	v_cmp_le_i32_e32 vcc, 0, v9
	s_or_b64 s[16:17], vcc, s[16:17]
	s_andn2_b64 exec, exec, s[16:17]
	s_cbranch_execnz .LBB0_964
	s_or_b64 exec, exec, s[16:17]
	s_movk_i32 s16, 0x2a00
	v_mad_i64_i32 v[38:39], s[16:17], v24, s16, v[16:17]
	global_load_dwordx2 v[38:39], v[38:39], off
	v_and_b32_e32 v9, 0x1fff, v24
	v_add_u32_e32 v9, 1, v9
	v_min_u32_e32 v9, v9, v19
	v_cvt_f32_ubyte0_e32 v9, v9
	v_div_scale_f32 v23, s[16:17], v9, v9, 1.0
	v_rcp_f32_e32 v27, v23
	v_ashrrev_i32_e32 v25, 31, v24
	v_fma_f32 v33, -v23, v27, 1.0
	v_fmac_f32_e32 v27, v33, v27
	v_div_scale_f32 v33, vcc, 1.0, v9, 1.0
	v_mul_f32_e32 v40, v33, v27
	v_fma_f32 v41, -v23, v40, v33
	v_fmac_f32_e32 v40, v41, v27
	v_fma_f32 v23, -v23, v40, v33
	v_div_fmas_f32 v23, v23, v27, v40
	v_div_fixup_f32 v40, v23, v9, 1.0
	s_waitcnt vmcnt(0)
	v_lshlrev_b32_e32 v64, 16, v38
	v_and_b32_e32 v65, 0xffff0000, v38
	v_lshlrev_b32_e32 v38, 16, v39
	v_and_b32_e32 v39, 0xffff0000, v39
	v_pk_fma_f32 v[36:37], v[40:41], v[36:37], v[64:65] op_sel_hi:[0,1,1] neg_lo:[0,0,1] neg_hi:[0,0,1]
	v_pk_fma_f32 v[34:35], v[40:41], v[34:35], v[38:39] op_sel_hi:[0,1,1] neg_lo:[0,0,1] neg_hi:[0,0,1]
	v_cvt_pk_bf16_f32 v36, v36, v37
	v_cvt_pk_bf16_f32 v37, v34, v35
	v_lshlrev_b64 v[34:35], 11, v[24:25]
	v_lshl_add_u64 v[34:35], v[14:15], 0, v[34:35]
	global_store_dwordx2 v[34:35], v[36:37], off

; template <int EPI>
; DI void gemm_unit(const GemmP& g, int pm, int pn) {
;     ...
;             f32x4 v = acc[ai][bj][m][n];
;             if (EPI == EPI_BF16) {
;               if (col >= g.aux_n0) {
;                 const int c2 = col - g.aux_n0;
;                 if (c2 < g.aux_cnt) *(f32x4*)(g.aux + (size_t)row * 16 + c2) = v * g.aux_scale;
; DI void run_phase(const Params& p, int ph, char* smem) {
;     ...
;       GemmP g1 = mk_gemm(XB, DM, (const u16*)(ws + (even ? O_EVIN + j * SZ_EVIN : O_ODIN + j * SZ_ODIN)), DM, DM, 64, even ? EV_N / 256 : OD_N / 256);
;       g1.Cb = (u16*)(ws + O_H); g1.ldc = HLD; g1.aux = (float*)(ws + O_AUX);
;       if (even) { g1.aux_n0 = 4160; g1.aux_cnt = 16; g1.aux_scale = 0.25f; } else { g1.aux_n0 = 5120; g1.aux_cnt = 8; g1.aux_scale = 1.f; }
.LBB0_985:
	v_lshrrev_b32_e32 v2, 6, v201
	v_and_b32_e32 v3, 15, v201
	v_bfe_u32 v4, v201, 4, 2
	v_readlane_b32 s14, v254, 0
	v_readfirstlane_b32 s15, v2
	s_cmp_gt_u32 s15, 3
	s_cbranch_scc1 .Lfg_done
	s_lshl_b32 s14, s14, 6
	v_lshl_add_u32 v5, v2, 4, v3
	v_add_u32_e32 v5, s14, v5
	v_lshlrev_b32_e32 v6, 4, v4
	v_lshl_or_b32 v8, v5, 12, v6
	v_lshl_or_b32 v9, v3, 12, v6
	v_lshl_or_b32 v7, v5, 6, v6
	s_add_u32 s16, s90, 0x1a500000
	s_addc_u32 s17, s91, 0
	s_mul_i32 s22, s58, 0x1500000
	s_mul_hi_i32 s23, s58, 0x1500000
	s_add_u32 s18, s90, s22
	s_addc_u32 s19, s91, s23
	s_add_u32 s18, s18, 0x4f00000
	s_addc_u32 s19, s19, 0
	s_add_u32 s20, s90, 0x39300000
	s_addc_u32 s21, s91, 0
	v_mov_b32_e32 v10, 0
	v_mov_b32_e32 v11, 0
	v_mov_b32_e32 v12, 0
	v_mov_b32_e32 v13, 0
	global_load_dwordx4 v[16:19], v8, s[16:17]
	global_load_dwordx4 v[20:23], v9, s[18:19]
	global_load_dwordx4 v[24:27], v8, s[16:17] offset:64
	global_load_dwordx4 v[28:31], v9, s[18:19] offset:64
	global_load_dwordx4 v[32:35], v8, s[16:17] offset:128
	global_load_dwordx4 v[36:39], v9, s[18:19] offset:128
	global_load_dwordx4 v[40:43], v8, s[16:17] offset:192
	global_load_dwordx4 v[44:47], v9, s[18:19] offset:192
	global_load_dwordx4 v[48:51], v8, s[16:17] offset:256
	global_load_dwordx4 v[52:55], v9, s[18:19] offset:256
	global_load_dwordx4 v[56:59], v8, s[16:17] offset:320
	global_load_dwordx4 v[60:63], v9, s[18:19] offset:320
	global_load_dwordx4 v[64:67], v8, s[16:17] offset:384
	global_load_dwordx4 v[68:71], v9, s[18:19] offset:384
	global_load_dwordx4 v[72:75], v8, s[16:17] offset:448
	global_load_dwordx4 v[76:79], v9, s[18:19] offset:448
	global_load_dwordx4 v[80:83], v8, s[16:17] offset:512
	global_load_dwordx4 v[84:87], v9, s[18:19] offset:512
	global_load_dwordx4 v[88:91], v8, s[16:17] offset:576
	global_load_dwordx4 v[92:95], v9, s[18:19] offset:576
	global_load_dwordx4 v[96:99], v8, s[16:17] offset:640
	global_load_dwordx4 v[100:103], v9, s[18:19] offset:640
	global_load_dwordx4 v[104:107], v8, s[16:17] offset:704
	global_load_dwordx4 v[108:111], v9, s[18:19] offset:704
	global_load_dwordx4 v[112:115], v8, s[16:17] offset:768
	global_load_dwordx4 v[116:119], v9, s[18:19] offset:768
	global_load_dwordx4 v[120:123], v8, s[16:17] offset:832
	global_load_dwordx4 v[124:127], v9, s[18:19] offset:832
	global_load_dwordx4 v[128:131], v8, s[16:17] offset:896
	global_load_dwordx4 v[132:135], v9, s[18:19] offset:896
	global_load_dwordx4 v[136:139], v8, s[16:17] offset:960
	global_load_dwordx4 v[140:143], v9, s[18:19] offset:960
	s_waitcnt vmcnt(16)
	v_mfma_f32_16x16x32_bf16 v[10:13], v[20:23], v[16:19], v[10:13]
	v_mfma_f32_16x16x32_bf16 v[10:13], v[28:31], v[24:27], v[10:13]
	v_mfma_f32_16x16x32_bf16 v[10:13], v[36:39], v[32:35], v[10:13]
	v_mfma_f32_16x16x32_bf16 v[10:13], v[44:47], v[40:43], v[10:13]
	v_mfma_f32_16x16x32_bf16 v[10:13], v[52:55], v[48:51], v[10:13]
	v_mfma_f32_16x16x32_bf16 v[10:13], v[60:63], v[56:59], v[10:13]
	v_mfma_f32_16x16x32_bf16 v[10:13], v[68:71], v[64:67], v[10:13]
	v_mfma_f32_16x16x32_bf16 v[10:13], v[76:79], v[72:75], v[10:13]
	global_load_dwordx4 v[16:19], v8, s[16:17] offset:1024
	global_load_dwordx4 v[20:23], v9, s[18:19] offset:1024
	global_load_dwordx4 v[24:27], v8, s[16:17] offset:1088
	global_load_dwordx4 v[28:31], v9, s[18:19] offset:1088
	global_load_dwordx4 v[32:35], v8, s[16:17] offset:1152
	global_load_dwordx4 v[36:39], v9, s[18:19] offset:1152
	global_load_dwordx4 v[40:43], v8, s[16:17] offset:1216
	global_load_dwordx4 v[44:47], v9, s[18:19] offset:1216
	global_load_dwordx4 v[48:51], v8, s[16:17] offset:1280
	global_load_dwordx4 v[52:55], v9, s[18:19] offset:1280
	global_load_dwordx4 v[56:59], v8, s[16:17] offset:1344
	global_load_dwordx4 v[60:63], v9, s[18:19] offset:1344
	global_load_dwordx4 v[64:67], v8, s[16:17] offset:1408
	global_load_dwordx4 v[68:71], v9, s[18:19] offset:1408
	global_load_dwordx4 v[72:75], v8, s[16:17] offset:1472
	global_load_dwordx4 v[76:79], v9, s[18:19] offset:1472
	s_waitcnt vmcnt(16)
	v_mfma_f32_16x16x32_bf16 v[10:13], v[84:87], v[80:83], v[10:13]
	v_mfma_f32_16x16x32_bf16 v[10:13], v[92:95], v[88:91], v[10:13]
	v_mfma_f32_16x16x32_bf16 v[10:13], v[100:103], v[96:99], v[10:13]
	v_mfma_f32_16x16x32_bf16 v[10:13], v[108:111], v[104:107], v[10:13]
	v_mfma_f32_16x16x32_bf16 v[10:13], v[116:119], v[112:115], v[10:13]
	v_mfma_f32_16x16x32_bf16 v[10:13], v[124:127], v[120:123], v[10:13]
	v_mfma_f32_16x16x32_bf16 v[10:13], v[132:135], v[128:131], v[10:13]
	v_mfma_f32_16x16x32_bf16 v[10:13], v[140:143], v[136:139], v[10:13]
	global_load_dwordx4 v[80:83], v8, s[16:17] offset:1536
	global_load_dwordx4 v[84:87], v9, s[18:19] offset:1536
	global_load_dwordx4 v[88:91], v8, s[16:17] offset:1600
	global_load_dwordx4 v[92:95], v9, s[18:19] offset:1600
	global_load_dwordx4 v[96:99], v8, s[16:17] offset:1664
	global_load_dwordx4 v[100:103], v9, s[18:19] offset:1664
	global_load_dwordx4 v[104:107], v8, s[16:17] offset:1728
	global_load_dwordx4 v[108:111], v9, s[18:19] offset:1728
	global_load_dwordx4 v[112:115], v8, s[16:17] offset:1792
	global_load_dwordx4 v[116:119], v9, s[18:19] offset:1792
	global_load_dwordx4 v[120:123], v8, s[16:17] offset:1856
	global_load_dwordx4 v[124:127], v9, s[18:19] offset:1856
	global_load_dwordx4 v[128:131], v8, s[16:17] offset:1920
	global_load_dwordx4 v[132:135], v9, s[18:19] offset:1920
	global_load_dwordx4 v[136:139], v8, s[16:17] offset:1984
	global_load_dwordx4 v[140:143], v9, s[18:19] offset:1984
	s_waitcnt vmcnt(16)
; template <int EPI>
; DI void gemm_unit(const GemmP& g, int pm, int pn) {
;     ...
;             f32x4 v = acc[ai][bj][m][n];
;             if (EPI == EPI_BF16) {
;               if (col >= g.aux_n0) {
;                 const int c2 = col - g.aux_n0;
;                 if (c2 < g.aux_cnt) *(f32x4*)(g.aux + (size_t)row * 16 + c2) = v * g.aux_scale;
; DI void run_phase(const Params& p, int ph, char* smem) {
;     ...
;       GemmP g1 = mk_gemm(XB, DM, (const u16*)(ws + (even ? O_EVIN + j * SZ_EVIN : O_ODIN + j * SZ_ODIN)), DM, DM, 64, even ? EV_N / 256 : OD_N / 256);
;       g1.Cb = (u16*)(ws + O_H); g1.ldc = HLD; g1.aux = (float*)(ws + O_AUX);
;       if (even) { g1.aux_n0 = 4160; g1.aux_cnt = 16; g1.aux_scale = 0.25f; } else { g1.aux_n0 = 5120; g1.aux_cnt = 8; g1.aux_scale = 1.f; }
	v_mfma_f32_16x16x32_bf16 v[10:13], v[20:23], v[16:19], v[10:13]
	v_mfma_f32_16x16x32_bf16 v[10:13], v[28:31], v[24:27], v[10:13]
	v_mfma_f32_16x16x32_bf16 v[10:13], v[36:39], v[32:35], v[10:13]
	v_mfma_f32_16x16x32_bf16 v[10:13], v[44:47], v[40:43], v[10:13]
	v_mfma_f32_16x16x32_bf16 v[10:13], v[52:55], v[48:51], v[10:13]
	v_mfma_f32_16x16x32_bf16 v[10:13], v[60:63], v[56:59], v[10:13]
	v_mfma_f32_16x16x32_bf16 v[10:13], v[68:71], v[64:67], v[10:13]
	v_mfma_f32_16x16x32_bf16 v[10:13], v[76:79], v[72:75], v[10:13]
	global_load_dwordx4 v[16:19], v8, s[16:17] offset:2048
	global_load_dwordx4 v[20:23], v9, s[18:19] offset:2048
	global_load_dwordx4 v[24:27], v8, s[16:17] offset:2112
	global_load_dwordx4 v[28:31], v9, s[18:19] offset:2112
	global_load_dwordx4 v[32:35], v8, s[16:17] offset:2176
	global_load_dwordx4 v[36:39], v9, s[18:19] offset:2176
	global_load_dwordx4 v[40:43], v8, s[16:17] offset:2240
	global_load_dwordx4 v[44:47], v9, s[18:19] offset:2240
	global_load_dwordx4 v[48:51], v8, s[16:17] offset:2304
	global_load_dwordx4 v[52:55], v9, s[18:19] offset:2304
	global_load_dwordx4 v[56:59], v8, s[16:17] offset:2368
	global_load_dwordx4 v[60:63], v9, s[18:19] offset:2368
	global_load_dwordx4 v[64:67], v8, s[16:17] offset:2432
	global_load_dwordx4 v[68:71], v9, s[18:19] offset:2432
	global_load_dwordx4 v[72:75], v8, s[16:17] offset:2496
	global_load_dwordx4 v[76:79], v9, s[18:19] offset:2496
	s_waitcnt vmcnt(16)
	v_mfma_f32_16x16x32_bf16 v[10:13], v[84:87], v[80:83], v[10:13]
	v_mfma_f32_16x16x32_bf16 v[10:13], v[92:95], v[88:91], v[10:13]
	v_mfma_f32_16x16x32_bf16 v[10:13], v[100:103], v[96:99], v[10:13]
	v_mfma_f32_16x16x32_bf16 v[10:13], v[108:111], v[104:107], v[10:13]
	v_mfma_f32_16x16x32_bf16 v[10:13], v[116:119], v[112:115], v[10:13]
	v_mfma_f32_16x16x32_bf16 v[10:13], v[124:127], v[120:123], v[10:13]
	v_mfma_f32_16x16x32_bf16 v[10:13], v[132:135], v[128:131], v[10:13]
	v_mfma_f32_16x16x32_bf16 v[10:13], v[140:143], v[136:139], v[10:13]
	global_load_dwordx4 v[80:83], v8, s[16:17] offset:2560
	global_load_dwordx4 v[84:87], v9, s[18:19] offset:2560
	global_load_dwordx4 v[88:91], v8, s[16:17] offset:2624
	global_load_dwordx4 v[92:95], v9, s[18:19] offset:2624
	global_load_dwordx4 v[96:99], v8, s[16:17] offset:2688
	global_load_dwordx4 v[100:103], v9, s[18:19] offset:2688
	global_load_dwordx4 v[104:107], v8, s[16:17] offset:2752
	global_load_dwordx4 v[108:111], v9, s[18:19] offset:2752
	global_load_dwordx4 v[112:115], v8, s[16:17] offset:2816
	global_load_dwordx4 v[116:119], v9, s[18:19] offset:2816
	global_load_dwordx4 v[120:123], v8, s[16:17] offset:2880
	global_load_dwordx4 v[124:127], v9, s[18:19] offset:2880
	global_load_dwordx4 v[128:131], v8, s[16:17] offset:2944
	global_load_dwordx4 v[132:135], v9, s[18:19] offset:2944
	global_load_dwordx4 v[136:139], v8, s[16:17] offset:3008
	global_load_dwordx4 v[140:143], v9, s[18:19] offset:3008
	s_waitcnt vmcnt(16)
; template <int EPI>
; DI void gemm_unit(const GemmP& g, int pm, int pn) {
;     ...
;             f32x4 v = acc[ai][bj][m][n];
;             if (EPI == EPI_BF16) {
;               if (col >= g.aux_n0) {
;                 const int c2 = col - g.aux_n0;
;                 if (c2 < g.aux_cnt) *(f32x4*)(g.aux + (size_t)row * 16 + c2) = v * g.aux_scale;
; DI void run_phase(const Params& p, int ph, char* smem) {
;     ...
;   const int L = (ph - 1) / PH_PER_LAYER, sp = (ph - 1) % PH_PER_LAYER;
;   const int j = L >> 1; const bool even = (L & 1) == 0;
;   const float* resid = (L == 0) ? p.x : nullptr;
;   const GemmP gz = mk_gemm(nullptr, 0, nullptr, 0, 0, 0, 0);
;   switch (sp) {
;     case 0: {
;       GemmP g1 = mk_gemm(XB, DM, (const u16*)(ws + (even ? O_EVIN + j * SZ_EVIN : O_ODIN + j * SZ_ODIN)), DM, DM, 64, even ? EV_N / 256 : OD_N / 256);
;       g1.Cb = (u16*)(ws + O_H); g1.ldc = HLD; g1.aux = (float*)(ws + O_AUX);
;       if (even) { g1.aux_n0 = 4160; g1.aux_cnt = 16; g1.aux_scale = 0.25f; } else { g1.aux_n0 = 5120; g1.aux_cnt = 8; g1.aux_scale = 1.f; }
	v_mfma_f32_16x16x32_bf16 v[10:13], v[20:23], v[16:19], v[10:13]
	v_mfma_f32_16x16x32_bf16 v[10:13], v[28:31], v[24:27], v[10:13]
	v_mfma_f32_16x16x32_bf16 v[10:13], v[36:39], v[32:35], v[10:13]
	v_mfma_f32_16x16x32_bf16 v[10:13], v[44:47], v[40:43], v[10:13]
	v_mfma_f32_16x16x32_bf16 v[10:13], v[52:55], v[48:51], v[10:13]
	v_mfma_f32_16x16x32_bf16 v[10:13], v[60:63], v[56:59], v[10:13]
	v_mfma_f32_16x16x32_bf16 v[10:13], v[68:71], v[64:67], v[10:13]
	v_mfma_f32_16x16x32_bf16 v[10:13], v[76:79], v[72:75], v[10:13]
	global_load_dwordx4 v[16:19], v8, s[16:17] offset:3072
	global_load_dwordx4 v[20:23], v9, s[18:19] offset:3072
	global_load_dwordx4 v[24:27], v8, s[16:17] offset:3136
	global_load_dwordx4 v[28:31], v9, s[18:19] offset:3136
	global_load_dwordx4 v[32:35], v8, s[16:17] offset:3200
	global_load_dwordx4 v[36:39], v9, s[18:19] offset:3200
	global_load_dwordx4 v[40:43], v8, s[16:17] offset:3264
	global_load_dwordx4 v[44:47], v9, s[18:19] offset:3264
	global_load_dwordx4 v[48:51], v8, s[16:17] offset:3328
	global_load_dwordx4 v[52:55], v9, s[18:19] offset:3328
	global_load_dwordx4 v[56:59], v8, s[16:17] offset:3392
	global_load_dwordx4 v[60:63], v9, s[18:19] offset:3392
	global_load_dwordx4 v[64:67], v8, s[16:17] offset:3456
	global_load_dwordx4 v[68:71], v9, s[18:19] offset:3456
	global_load_dwordx4 v[72:75], v8, s[16:17] offset:3520
	global_load_dwordx4 v[76:79], v9, s[18:19] offset:3520
	s_waitcnt vmcnt(16)
	v_mfma_f32_16x16x32_bf16 v[10:13], v[84:87], v[80:83], v[10:13]
	v_mfma_f32_16x16x32_bf16 v[10:13], v[92:95], v[88:91], v[10:13]
	v_mfma_f32_16x16x32_bf16 v[10:13], v[100:103], v[96:99], v[10:13]
	v_mfma_f32_16x16x32_bf16 v[10:13], v[108:111], v[104:107], v[10:13]
	v_mfma_f32_16x16x32_bf16 v[10:13], v[116:119], v[112:115], v[10:13]
	v_mfma_f32_16x16x32_bf16 v[10:13], v[124:127], v[120:123], v[10:13]
	v_mfma_f32_16x16x32_bf16 v[10:13], v[132:135], v[128:131], v[10:13]
	v_mfma_f32_16x16x32_bf16 v[10:13], v[140:143], v[136:139], v[10:13]
	global_load_dwordx4 v[80:83], v8, s[16:17] offset:3584
	global_load_dwordx4 v[84:87], v9, s[18:19] offset:3584
	global_load_dwordx4 v[88:91], v8, s[16:17] offset:3648
	global_load_dwordx4 v[92:95], v9, s[18:19] offset:3648
	global_load_dwordx4 v[96:99], v8, s[16:17] offset:3712
	global_load_dwordx4 v[100:103], v9, s[18:19] offset:3712
	global_load_dwordx4 v[104:107], v8, s[16:17] offset:3776
	global_load_dwordx4 v[108:111], v9, s[18:19] offset:3776
	global_load_dwordx4 v[112:115], v8, s[16:17] offset:3840
	global_load_dwordx4 v[116:119], v9, s[18:19] offset:3840
	global_load_dwordx4 v[120:123], v8, s[16:17] offset:3904
	global_load_dwordx4 v[124:127], v9, s[18:19] offset:3904
	global_load_dwordx4 v[128:131], v8, s[16:17] offset:3968
	global_load_dwordx4 v[132:135], v9, s[18:19] offset:3968
	global_load_dwordx4 v[136:139], v8, s[16:17] offset:4032
	global_load_dwordx4 v[140:143], v9, s[18:19] offset:4032
	s_waitcnt vmcnt(16)
	v_mfma_f32_16x16x32_bf16 v[10:13], v[20:23], v[16:19], v[10:13]
	v_mfma_f32_16x16x32_bf16 v[10:13], v[28:31], v[24:27], v[10:13]
	v_mfma_f32_16x16x32_bf16 v[10:13], v[36:39], v[32:35], v[10:13]
	v_mfma_f32_16x16x32_bf16 v[10:13], v[44:47], v[40:43], v[10:13]
	v_mfma_f32_16x16x32_bf16 v[10:13], v[52:55], v[48:51], v[10:13]
	v_mfma_f32_16x16x32_bf16 v[10:13], v[60:63], v[56:59], v[10:13]
	v_mfma_f32_16x16x32_bf16 v[10:13], v[68:71], v[64:67], v[10:13]
	v_mfma_f32_16x16x32_bf16 v[10:13], v[76:79], v[72:75], v[10:13]
	s_waitcnt vmcnt(0)
	v_mfma_f32_16x16x32_bf16 v[10:13], v[84:87], v[80:83], v[10:13]
	v_mfma_f32_16x16x32_bf16 v[10:13], v[92:95], v[88:91], v[10:13]
	v_mfma_f32_16x16x32_bf16 v[10:13], v[100:103], v[96:99], v[10:13]
	v_mfma_f32_16x16x32_bf16 v[10:13], v[108:111], v[104:107], v[10:13]
	v_mfma_f32_16x16x32_bf16 v[10:13], v[116:119], v[112:115], v[10:13]
	v_mfma_f32_16x16x32_bf16 v[10:13], v[124:127], v[120:123], v[10:13]
	v_mfma_f32_16x16x32_bf16 v[10:13], v[132:135], v[128:131], v[10:13]
	v_mfma_f32_16x16x32_bf16 v[10:13], v[140:143], v[136:139], v[10:13]
	s_nop 7
	s_nop 1
	v_cmp_gt_u32_e32 vcc, 2, v4
	s_and_saveexec_b64 s[14:15], vcc
	global_store_dwordx4 v7, v[10:13], s[20:21]
	s_or_b64 exec, exec, s[14:15]
.Lfg_done:
	s_mov_b32 s16, 1.0
	s_mov_b32 s8, 20
	s_movk_i32 s39, 0x1400
	s_mov_b32 s44, 8
	s_mov_b64 s[6:7], 0x6500000
